# combo15 + P1 first-operand rows: the next row's x chunks prefetched while the current row is scaled and stored
# speedup vs baseline: 1.0013x; 1.0013x over previous
; #define GAS __attribute__((address_space(1)))
; __device__ __forceinline__ unsigned cvt_pk_bf16(float lo, float hi) { unsigned r; asm volatile("v_cvt_pk_bf16_f32 %0, %1, %2" : "=v"(r) : "v"(lo), "v"(hi)); return r; }
; __device__ __forceinline__ void phase_weights(LAS unsigned char* lds, const Ptrs& P, int wg, int G, int wv) {
;     ...
;         for (int r = gw; r < M; r += NGW) {
;             const int b = r >> 12;
;             const GAS float* xr = (const GAS float*)P.x + (size_t)r * D + 8 * lane;
;             f32x4 v[4][2]; float ss = 0.f;
; #pragma unroll
;             for (int j = 0; j < 4; ++j)
; #pragma unroll
;                 for (int h = 0; h < 2; ++h) { v[j][h] = *(const GAS f32x4*)(xr + 512 * j + 4 * h); ss += (v[j][h][0] * v[j][h][0] + v[j][h][1] * v[j][h][1]) + (v[j][h][2] * v[j][h][2] + v[j][h][3] * v[j][h][3]); }
;             ss = wave_sum(ss);
;             if (lane < 8) rowss0[(size_t)r * 8 + lane] = lane == 0 ? ss : 0.f;
;             const float sr8 = 127.0f / (ACT_CLIP * __builtin_sqrtf(ss * INV_D + 1e-20f));
; #pragma unroll
;             for (int j = 0; j < 4; ++j) {
;                 const int cidx = 8 * lane + 512 * j;
;                 u32x4 w; unsigned w8[2] = {0u, 0u};
; #pragma unroll
;                 for (int h = 0; h < 2; ++h) {
;                     const f32x4 a = *(const GAS f32x4*)((const GAS float*)P.norm_ffn1 + cidx + 4 * h) * (*(const GAS f32x4*)((const GAS float*)mods + (size_t)b * MODS_LD + D + cidx + 4 * h) + 1.0f);
;                     const f32x4 o = v[j][h] * a;
;                     if (h == 0) { w.x = cvt_pk_bf16(o[0], o[1]); w.y = cvt_pk_bf16(o[2], o[3]); } else { w.z = cvt_pk_bf16(o[0], o[1]); w.w = cvt_pk_bf16(o[2], o[3]); }
;                     if (USE_I8) { const f32x4 oq = o * sr8; w8[h] = cvt_i8x4(oq[0], oq[1], oq[2], oq[3]); }
;                 }
;                 if (!USE_I8) *(GAS u32x4*)(xa + pg8::img_chunk(r, cidx >> 3, KT_D)) = w;
.LBB0_79:
	s_or_b64 exec, exec, s[0:1]
	v_readlane_b32 s0, v254, 1
	s_waitcnt lgkmcnt(0)
	s_barrier
	v_mbcnt_lo_u32_b32 v0, -1, 0
	v_mbcnt_hi_u32_b32 v0, -1, v0
	s_lshl_b32 s10, s2, 3
	v_lshl_add_u32 v0, s0, 6, v0
	s_nop 0
	v_readfirstlane_b32 s0, v0
	s_ashr_i32 s9, s0, 6
	s_add_i32 s30, s9, s10
	s_cmpk_gt_i32 s30, 0x3fff
	s_cbranch_scc1 .LBB0_84
	v_and_b32_e32 v1, 63, v0
	v_lshlrev_b32_e32 v2, 3, v1
	v_mov_b32_e32 v33, 0
	v_or_b32_e32 v4, 0x400, v2
	s_lshl_b32 s8, s84, 3
	v_or_b32_e32 v6, 0x600, v2
	v_lshlrev_b32_e32 v8, 2, v4
	v_mov_b32_e32 v9, v33
	s_add_u32 s31, s92, 0x49400000
	v_lshlrev_b32_e32 v32, 5, v1
	v_lshl_add_u64 v[44:45], s[6:7], 0, v[8:9]
	v_lshlrev_b32_e32 v8, 2, v6
	s_addc_u32 s34, s93, 0
	v_lshl_add_u64 v[42:43], s[6:7], 0, v[32:33]
	v_lshl_add_u64 v[46:47], s[6:7], 0, v[8:9]
	s_ashr_i32 s7, s9, 31
	s_ashr_i32 s11, s10, 31
	s_add_u32 s6, s9, s10
	s_addc_u32 s7, s7, s11
	s_lshl_b64 s[10:11], s[6:7], 5
	s_add_u32 s10, s92, s10
	v_lshlrev_b32_e32 v8, 2, v1
	s_addc_u32 s11, s93, s11
	v_bfe_u32 v52, v0, 3, 1
	v_lshlrev_b32_e32 v0, 10, v0
	v_lshl_add_u64 v[8:9], s[10:11], 0, v[8:9]
	s_mov_b64 s[10:11], 0x140000
	s_ashr_i32 s9, s8, 31
	v_and_b32_e32 v34, 0xc000, v0
	v_or_b32_e32 v0, 0x200, v2
	v_lshl_add_u64 v[48:49], v[8:9], 0, s[10:11]
	s_lshl_b64 s[10:11], s[8:9], 5
	s_lshl_b64 s[6:7], s[6:7], 13
	v_lshlrev_b32_e32 v3, 7, v0
	s_add_u32 s6, s24, s6
	v_and_b32_e32 v36, 0x1c000, v3
	v_lshlrev_b32_e32 v3, 7, v4
	s_addc_u32 s7, s25, s7
	v_and_b32_e32 v38, 0x2c000, v3
	v_lshlrev_b32_e32 v3, 7, v6
	v_lshl_add_u64 v[8:9], s[6:7], 0, v[32:33]
	s_mov_b64 s[6:7], 0x1000
	v_cmp_gt_u32_e64 s[0:1], 8, v1
	v_cmp_eq_u32_e64 s[4:5], 0, v1
	v_and_b32_e32 v53, 56, v2
	v_mov_b32_e32 v35, v33
	v_mov_b32_e32 v37, v33
	v_mov_b32_e32 v39, v33
	v_and_b32_e32 v40, 0x3c000, v3
	v_mov_b32_e32 v41, v33
	v_lshl_add_u64 v[50:51], v[8:9], 0, s[6:7]
	s_lshl_b64 s[24:25], s[8:9], 13
	v_mov_b32_e32 v54, 0x1e3ce508
	s_mov_b32 s9, 0xf800000
	v_mov_b32_e32 v55, 0x260
	s_mov_b32 s35, 0x42fe0000
	v_lshlrev_b32_e32 v56, 2, v2
	v_lshlrev_b32_e32 v57, 2, v0
	v_lshlrev_b32_e32 v58, 2, v4
	v_lshlrev_b32_e32 v59, 2, v6
	global_load_dwordx4 v[100:103], v[50:51], off offset:-4096
	global_load_dwordx4 v[104:107], v[50:51], off offset:-4080
	global_load_dwordx4 v[108:111], v[50:51], off offset:-2048
	global_load_dwordx4 v[112:115], v[50:51], off offset:-2032
	global_load_dwordx4 v[116:119], v[50:51], off
	global_load_dwordx4 v[120:123], v[50:51], off offset:16
	global_load_dwordx4 v[124:127], v[50:51], off offset:2048
	global_load_dwordx4 v[128:131], v[50:51], off offset:2064
	s_branch .LBB0_82
.LBB0_81:
	s_or_b64 exec, exec, s[6:7]
	s_waitcnt vmcnt(0)
	s_ashr_i32 s6, s30, 12
	s_mul_hi_i32 s7, s6, 0x12000
	s_mul_i32 s6, s6, 0x12000
	s_add_u32 s6, s33, s6
	s_addc_u32 s7, s38, s7
	s_add_u32 s26, s6, 0x2000
	s_addc_u32 s27, s7, 0
	s_nop 1
	v_mov_b32_e32 v60, v180
	v_mov_b32_e32 v61, v181
	v_mov_b32_e32 v62, v182
	v_mov_b32_e32 v63, v183
	s_nop 1
	v_mov_b32_e32 v64, v212
	v_mov_b32_e32 v65, v213
	v_mov_b32_e32 v66, v214
	v_mov_b32_e32 v67, v215
	s_ashr_i32 s6, s30, 7
	s_and_b32 s36, s30, 15
	s_ashr_i32 s7, s6, 31
	v_lshl_add_u64 v[48:49], v[48:49], 0, s[10:11]
	v_lshl_add_u64 v[50:51], v[50:51], 0, s[24:25]
	v_pk_add_f32 v[62:63], v[62:63], 1.0 op_sel_hi:[1,0]
	v_pk_add_f32 v[60:61], v[60:61], 1.0 op_sel_hi:[1,0]
	v_pk_mul_f32 v[62:63], v[66:67], v[62:63]
	v_pk_mul_f32 v[60:61], v[64:65], v[60:61]
	v_pk_mul_f32 v[68:69], v[30:31], v[62:63]
	v_pk_mul_f32 v[70:71], v[28:29], v[60:61]
	v_lshl_or_b32 v30, s36, 6, v53
	v_cvt_pk_bf16_f32 v28, v70, v71
	s_lshl_b64 s[36:37], s[6:7], 18
	v_cvt_pk_bf16_f32 v28, v68, v69
	s_nop 1
	v_mov_b32_e32 v60, v184
	v_mov_b32_e32 v61, v185
	v_mov_b32_e32 v62, v186
	v_mov_b32_e32 v63, v187
	s_nop 1
	v_mov_b32_e32 v64, v216
	v_mov_b32_e32 v65, v217
	v_mov_b32_e32 v66, v218
	v_mov_b32_e32 v67, v219
	v_fmamk_f32 v28, v32, 0x3a000000, v54
	v_mul_f32_e32 v29, 0x4f800000, v28
	v_cmp_gt_f32_e32 vcc, s9, v28
	s_add_u32 s36, s31, s36
	s_addc_u32 s37, s34, s37
	v_cndmask_b32_e32 v28, v28, v29, vcc
	v_sqrt_f32_e32 v29, v28
	s_lshr_b32 s39, s30, 3
	s_lshl_b32 s40, s30, 2
	s_add_i32 s30, s30, s8
	s_cmpk_gt_i32 s30, 0x3fff
	s_cbranch_scc1 .Lp1x_skip
	global_load_dwordx4 v[100:103], v[50:51], off offset:-4096
	global_load_dwordx4 v[104:107], v[50:51], off offset:-4080
	global_load_dwordx4 v[108:111], v[50:51], off offset:-2048
	global_load_dwordx4 v[112:115], v[50:51], off offset:-2032
	global_load_dwordx4 v[116:119], v[50:51], off
	global_load_dwordx4 v[120:123], v[50:51], off offset:16
	global_load_dwordx4 v[124:127], v[50:51], off offset:2048
	global_load_dwordx4 v[128:131], v[50:51], off offset:2064
; #define GAS __attribute__((address_space(1)))
; __device__ __forceinline__ unsigned cvt_pk_bf16(float lo, float hi) { unsigned r; asm volatile("v_cvt_pk_bf16_f32 %0, %1, %2" : "=v"(r) : "v"(lo), "v"(hi)); return r; }
; __device__ __forceinline__ void phase_weights(LAS unsigned char* lds, const Ptrs& P, int wg, int G, int wv) {
;     ...
;             for (int j = 0; j < 4; ++j) {
;                 const int cidx = 8 * lane + 512 * j;
;                 u32x4 w; unsigned w8[2] = {0u, 0u};
; #pragma unroll
;                 for (int h = 0; h < 2; ++h) {
;                     const f32x4 a = *(const GAS f32x4*)((const GAS float*)P.norm_ffn1 + cidx + 4 * h) * (*(const GAS f32x4*)((const GAS float*)mods + (size_t)b * MODS_LD + D + cidx + 4 * h) + 1.0f);
;                     const f32x4 o = v[j][h] * a;
;                     if (h == 0) { w.x = cvt_pk_bf16(o[0], o[1]); w.y = cvt_pk_bf16(o[2], o[3]); } else { w.z = cvt_pk_bf16(o[0], o[1]); w.w = cvt_pk_bf16(o[2], o[3]); }
;                     if (USE_I8) { const f32x4 oq = o * sr8; w8[h] = cvt_i8x4(oq[0], oq[1], oq[2], oq[3]); }
;                 }
;                 if (!USE_I8) *(GAS u32x4*)(xa + pg8::img_chunk(r, cidx >> 3, KT_D)) = w;
;                 else { const int rr = r & 15; u32x2 ww; ww.x = w8[0]; ww.y = w8[1];
;                     *(GAS u32x2*)((GAS char*)(ws + WS_XA8) + ((size_t)(r >> 7) * KT_D8 + (cidx >> 7)) * pg8::HTB + (size_t)((((r >> 4) & 7) * 2 + ((cidx >> 6) & 1)) * 1024 + ((rr * 64 + (cidx & 63)) ^ ((rr >> 3) << 5)))) = ww; }
.Lp1x_skip:
	v_add_u32_e32 v31, -1, v29
	v_add_u32_e32 v32, 1, v29
	v_fma_f32 v72, -v31, v29, v28
	v_fma_f32 v73, -v32, v29, v28
	v_cmp_ge_f32_e64 s[6:7], 0, v72
	v_pk_add_f32 v[60:61], v[60:61], 1.0 op_sel_hi:[1,0]
	v_cndmask_b32_e64 v29, v29, v31, s[6:7]
	v_cmp_lt_f32_e64 s[6:7], 0, v73
	v_and_or_b32 v31, s39, 14, v52
	v_lshlrev_b32_e32 v31, 10, v31
	v_cndmask_b32_e64 v29, v29, v32, s[6:7]
	v_mul_f32_e32 v32, 0x37800000, v29
	s_and_b32 s6, s40, 32
	v_cndmask_b32_e32 v29, v29, v32, vcc
	v_cmp_class_f32_e32 vcc, v28, v55
	v_bitop3_b32 v32, v31, v30, s6 bitop3:0xf6
	v_pk_add_f32 v[62:63], v[62:63], 1.0 op_sel_hi:[1,0]
	v_cndmask_b32_e32 v30, v29, v28, vcc
	v_mul_f32_e32 v30, 0x40c00000, v30
	v_div_scale_f32 v31, s[6:7], v30, v30, s35
	v_lshl_add_u64 v[28:29], s[36:37], 0, v[32:33]
	v_rcp_f32_e32 v32, v31
	v_div_scale_f32 v74, vcc, s35, v30, s35
	v_pk_mul_f32 v[60:61], v[64:65], v[60:61]
	v_fma_f32 v75, -v31, v32, 1.0
	v_fmac_f32_e32 v32, v75, v32
	v_mul_f32_e32 v75, v74, v32
	v_fma_f32 v76, -v31, v75, v74
	v_fmac_f32_e32 v75, v76, v32
	v_fma_f32 v31, -v31, v75, v74
	v_div_fmas_f32 v31, v31, v32, v75
	v_div_fixup_f32 v30, v31, v30, s35
	v_pk_mul_f32 v[70:71], v[30:31], v[70:71] op_sel_hi:[0,1]
	v_pk_mul_f32 v[68:69], v[30:31], v[68:69] op_sel_hi:[0,1]
	v_add_f32_e32 v31, 0x43000000, v70
	v_add_f32_e32 v32, 0x43000000, v71
	v_cvt_pk_u8_f32 v31, v31, 0, 0
	v_add_f32_e32 v68, 0x43000000, v68
	v_cvt_pk_u8_f32 v31, v32, 1, v31
	v_add_f32_e32 v69, 0x43000000, v69
	v_cvt_pk_u8_f32 v31, v68, 2, v31
	v_cvt_pk_u8_f32 v31, v69, 3, v31
	v_pk_mul_f32 v[62:63], v[66:67], v[62:63]
	v_pk_mul_f32 v[24:25], v[24:25], v[60:61]
	v_xor_b32_e32 v68, 0x80808080, v31
	v_pk_mul_f32 v[26:27], v[26:27], v[62:63]
	v_cvt_pk_bf16_f32 v31, v24, v25
	v_lshl_add_u64 v[72:73], v[28:29], 0, v[34:35]
	v_cvt_pk_bf16_f32 v31, v26, v27
	v_lshl_add_u64 v[64:65], v[28:29], 0, v[36:37]
	v_pk_mul_f32 v[24:25], v[30:31], v[24:25] op_sel_hi:[0,1]
	v_add_f32_e32 v24, 0x43000000, v24
	v_pk_mul_f32 v[26:27], v[30:31], v[26:27] op_sel_hi:[0,1]
	v_add_f32_e32 v25, 0x43000000, v25
	v_cvt_pk_u8_f32 v24, v24, 0, 0
	v_add_f32_e32 v26, 0x43000000, v26
	v_cvt_pk_u8_f32 v24, v25, 1, v24
	v_add_f32_e32 v27, 0x43000000, v27
	v_cvt_pk_u8_f32 v24, v26, 2, v24
	v_cvt_pk_u8_f32 v24, v27, 3, v24
	v_xor_b32_e32 v69, 0x80808080, v24
	global_store_dwordx2 v[72:73], v[68:69], off
	s_nop 1
	v_mov_b32_e32 v24, v188
	v_mov_b32_e32 v25, v189
	v_mov_b32_e32 v26, v190
	v_mov_b32_e32 v27, v191
	s_nop 1
	v_mov_b32_e32 v60, v220
	v_mov_b32_e32 v61, v221
	v_mov_b32_e32 v62, v222
	v_mov_b32_e32 v63, v223
	s_cmpk_gt_i32 s30, 0x3fff
	v_pk_add_f32 v[26:27], v[26:27], 1.0 op_sel_hi:[1,0]
	v_pk_add_f32 v[24:25], v[24:25], 1.0 op_sel_hi:[1,0]
	v_pk_mul_f32 v[26:27], v[62:63], v[26:27]
	v_pk_mul_f32 v[24:25], v[60:61], v[24:25]
	v_pk_mul_f32 v[60:61], v[22:23], v[26:27]
	v_pk_mul_f32 v[62:63], v[20:21], v[24:25]
	s_nop 0
	v_cvt_pk_bf16_f32 v20, v62, v63
	v_pk_mul_f32 v[62:63], v[30:31], v[62:63] op_sel_hi:[0,1]
	v_cvt_pk_bf16_f32 v20, v60, v61
	s_nop 1
	v_mov_b32_e32 v20, v192
	v_mov_b32_e32 v21, v193
	v_mov_b32_e32 v22, v194
	v_mov_b32_e32 v23, v195
	s_nop 1
	v_mov_b32_e32 v24, v224
	v_mov_b32_e32 v25, v225
	v_mov_b32_e32 v26, v226
	v_mov_b32_e32 v27, v227
	v_pk_mul_f32 v[60:61], v[30:31], v[60:61] op_sel_hi:[0,1]
	v_add_f32_e32 v31, 0x43000000, v62
	v_add_f32_e32 v32, 0x43000000, v63
	v_cvt_pk_u8_f32 v31, v31, 0, 0
	v_add_f32_e32 v60, 0x43000000, v60
	v_cvt_pk_u8_f32 v31, v32, 1, v31
	v_add_f32_e32 v61, 0x43000000, v61
	v_cvt_pk_u8_f32 v31, v60, 2, v31
	v_cvt_pk_u8_f32 v31, v61, 3, v31
	v_xor_b32_e32 v60, 0x80808080, v31
	v_pk_add_f32 v[20:21], v[20:21], 1.0 op_sel_hi:[1,0]
	v_pk_mul_f32 v[20:21], v[24:25], v[20:21]
	v_pk_add_f32 v[22:23], v[22:23], 1.0 op_sel_hi:[1,0]
	v_pk_mul_f32 v[16:17], v[16:17], v[20:21]
	v_pk_mul_f32 v[22:23], v[26:27], v[22:23]
	v_cvt_pk_bf16_f32 v20, v16, v17
	v_pk_mul_f32 v[16:17], v[30:31], v[16:17] op_sel_hi:[0,1]
	v_pk_mul_f32 v[18:19], v[18:19], v[22:23]
	v_add_f32_e32 v16, 0x43000000, v16
	v_cvt_pk_bf16_f32 v20, v18, v19
	v_pk_mul_f32 v[18:19], v[30:31], v[18:19] op_sel_hi:[0,1]
	v_add_f32_e32 v17, 0x43000000, v17
	v_cvt_pk_u8_f32 v16, v16, 0, 0
	v_add_f32_e32 v18, 0x43000000, v18
	v_cvt_pk_u8_f32 v16, v17, 1, v16
	v_add_f32_e32 v19, 0x43000000, v19
	v_cvt_pk_u8_f32 v16, v18, 2, v16
	v_cvt_pk_u8_f32 v16, v19, 3, v16
	v_xor_b32_e32 v61, 0x80808080, v16
	global_store_dwordx2 v[64:65], v[60:61], off
	s_nop 1
	v_mov_b32_e32 v16, v196
	v_mov_b32_e32 v17, v197
	v_mov_b32_e32 v18, v198
	v_mov_b32_e32 v19, v199
	s_nop 1
	v_mov_b32_e32 v20, v228
	v_mov_b32_e32 v21, v229
	v_mov_b32_e32 v22, v230
	v_mov_b32_e32 v23, v231
	v_lshl_add_u64 v[24:25], v[28:29], 0, v[38:39]
	v_pk_add_f32 v[18:19], v[18:19], 1.0 op_sel_hi:[1,0]
	v_pk_add_f32 v[16:17], v[16:17], 1.0 op_sel_hi:[1,0]
	v_pk_mul_f32 v[18:19], v[22:23], v[18:19]
	v_pk_mul_f32 v[16:17], v[20:21], v[16:17]
	v_pk_mul_f32 v[20:21], v[14:15], v[18:19]
	v_pk_mul_f32 v[22:23], v[12:13], v[16:17]
	s_nop 0
	v_cvt_pk_bf16_f32 v12, v22, v23
	v_pk_mul_f32 v[22:23], v[30:31], v[22:23] op_sel_hi:[0,1]
	v_cvt_pk_bf16_f32 v12, v20, v21
	s_nop 1
	v_mov_b32_e32 v12, v200
	v_mov_b32_e32 v13, v201
	v_mov_b32_e32 v14, v202
	v_mov_b32_e32 v15, v203
	s_nop 1
	v_mov_b32_e32 v16, v232
	v_mov_b32_e32 v17, v233
	v_mov_b32_e32 v18, v234
	v_mov_b32_e32 v19, v235
	v_add_f32_e32 v22, 0x43000000, v22
	v_pk_mul_f32 v[20:21], v[30:31], v[20:21] op_sel_hi:[0,1]
	v_add_f32_e32 v23, 0x43000000, v23
	v_cvt_pk_u8_f32 v22, v22, 0, 0
	v_add_f32_e32 v20, 0x43000000, v20
	v_cvt_pk_u8_f32 v22, v23, 1, v22
	v_add_f32_e32 v21, 0x43000000, v21
	v_cvt_pk_u8_f32 v20, v20, 2, v22
; #define GAS __attribute__((address_space(1)))
; __device__ __forceinline__ unsigned cvt_pk_bf16(float lo, float hi) { unsigned r; asm volatile("v_cvt_pk_bf16_f32 %0, %1, %2" : "=v"(r) : "v"(lo), "v"(hi)); return r; }
; __device__ __forceinline__ void phase_weights(LAS unsigned char* lds, const Ptrs& P, int wg, int G, int wv) {
;     ...
;             for (int j = 0; j < 4; ++j) {
;                 const int cidx = 8 * lane + 512 * j;
;                 u32x4 w; unsigned w8[2] = {0u, 0u};
; #pragma unroll
;                 for (int h = 0; h < 2; ++h) {
;                     const f32x4 a = *(const GAS f32x4*)((const GAS float*)P.norm_ffn1 + cidx + 4 * h) * (*(const GAS f32x4*)((const GAS float*)mods + (size_t)b * MODS_LD + D + cidx + 4 * h) + 1.0f);
;                     const f32x4 o = v[j][h] * a;
;                     if (h == 0) { w.x = cvt_pk_bf16(o[0], o[1]); w.y = cvt_pk_bf16(o[2], o[3]); } else { w.z = cvt_pk_bf16(o[0], o[1]); w.w = cvt_pk_bf16(o[2], o[3]); }
;                     if (USE_I8) { const f32x4 oq = o * sr8; w8[h] = cvt_i8x4(oq[0], oq[1], oq[2], oq[3]); }
;                 }
;                 if (!USE_I8) *(GAS u32x4*)(xa + pg8::img_chunk(r, cidx >> 3, KT_D)) = w;
;                 else { const int rr = r & 15; u32x2 ww; ww.x = w8[0]; ww.y = w8[1];
;                     *(GAS u32x2*)((GAS char*)(ws + WS_XA8) + ((size_t)(r >> 7) * KT_D8 + (cidx >> 7)) * pg8::HTB + (size_t)((((r >> 4) & 7) * 2 + ((cidx >> 6) & 1)) * 1024 + ((rr * 64 + (cidx & 63)) ^ ((rr >> 3) << 5)))) = ww; }
	v_cvt_pk_u8_f32 v20, v21, 3, v20
	v_xor_b32_e32 v20, 0x80808080, v20
	v_pk_add_f32 v[12:13], v[12:13], 1.0 op_sel_hi:[1,0]
	v_pk_mul_f32 v[12:13], v[16:17], v[12:13]
	v_pk_add_f32 v[14:15], v[14:15], 1.0 op_sel_hi:[1,0]
	v_pk_mul_f32 v[8:9], v[8:9], v[12:13]
	v_pk_mul_f32 v[14:15], v[18:19], v[14:15]
	v_cvt_pk_bf16_f32 v12, v8, v9
	v_pk_mul_f32 v[8:9], v[30:31], v[8:9] op_sel_hi:[0,1]
	v_pk_mul_f32 v[10:11], v[10:11], v[14:15]
	v_add_f32_e32 v8, 0x43000000, v8
	v_cvt_pk_bf16_f32 v12, v10, v11
	v_pk_mul_f32 v[10:11], v[30:31], v[10:11] op_sel_hi:[0,1]
	v_add_f32_e32 v9, 0x43000000, v9
	v_cvt_pk_u8_f32 v8, v8, 0, 0
	v_add_f32_e32 v10, 0x43000000, v10
	v_cvt_pk_u8_f32 v8, v9, 1, v8
	v_add_f32_e32 v11, 0x43000000, v11
	v_cvt_pk_u8_f32 v8, v10, 2, v8
	v_cvt_pk_u8_f32 v8, v11, 3, v8
	v_xor_b32_e32 v21, 0x80808080, v8
	global_store_dwordx2 v[24:25], v[20:21], off
	s_nop 1
	v_mov_b32_e32 v8, v204
	v_mov_b32_e32 v9, v205
	v_mov_b32_e32 v10, v206
	v_mov_b32_e32 v11, v207
	s_nop 1
	v_mov_b32_e32 v12, v236
	v_mov_b32_e32 v13, v237
	v_mov_b32_e32 v14, v238
	v_mov_b32_e32 v15, v239
	v_lshl_add_u64 v[16:17], v[28:29], 0, v[40:41]
	v_pk_add_f32 v[10:11], v[10:11], 1.0 op_sel_hi:[1,0]
	v_pk_add_f32 v[8:9], v[8:9], 1.0 op_sel_hi:[1,0]
	v_pk_mul_f32 v[10:11], v[14:15], v[10:11]
	v_pk_mul_f32 v[8:9], v[12:13], v[8:9]
	v_pk_mul_f32 v[12:13], v[6:7], v[10:11]
	v_pk_mul_f32 v[14:15], v[4:5], v[8:9]
	s_nop 0
	v_cvt_pk_bf16_f32 v4, v14, v15
	v_pk_mul_f32 v[14:15], v[30:31], v[14:15] op_sel_hi:[0,1]
	v_cvt_pk_bf16_f32 v4, v12, v13
	s_nop 1
	v_mov_b32_e32 v4, v208
	v_mov_b32_e32 v5, v209
	v_mov_b32_e32 v6, v210
	v_mov_b32_e32 v7, v211
	s_nop 1
	v_mov_b32_e32 v8, v240
	v_mov_b32_e32 v9, v241
	v_mov_b32_e32 v10, v242
	v_mov_b32_e32 v11, v243
	v_add_f32_e32 v14, 0x43000000, v14
	v_pk_mul_f32 v[12:13], v[30:31], v[12:13] op_sel_hi:[0,1]
	v_add_f32_e32 v15, 0x43000000, v15
	v_cvt_pk_u8_f32 v14, v14, 0, 0
	v_add_f32_e32 v12, 0x43000000, v12
	v_cvt_pk_u8_f32 v14, v15, 1, v14
	v_add_f32_e32 v13, 0x43000000, v13
	v_cvt_pk_u8_f32 v12, v12, 2, v14
	v_cvt_pk_u8_f32 v12, v13, 3, v12
	v_xor_b32_e32 v12, 0x80808080, v12
	v_pk_add_f32 v[4:5], v[4:5], 1.0 op_sel_hi:[1,0]
	v_pk_mul_f32 v[4:5], v[8:9], v[4:5]
	v_pk_add_f32 v[6:7], v[6:7], 1.0 op_sel_hi:[1,0]
	v_pk_mul_f32 v[0:1], v[0:1], v[4:5]
	v_pk_mul_f32 v[6:7], v[10:11], v[6:7]
	v_cvt_pk_bf16_f32 v4, v0, v1
	v_pk_mul_f32 v[0:1], v[30:31], v[0:1] op_sel_hi:[0,1]
	v_pk_mul_f32 v[2:3], v[2:3], v[6:7]
	v_add_f32_e32 v0, 0x43000000, v0
	v_cvt_pk_bf16_f32 v4, v2, v3
	v_pk_mul_f32 v[2:3], v[30:31], v[2:3] op_sel_hi:[0,1]
	v_add_f32_e32 v1, 0x43000000, v1
	v_cvt_pk_u8_f32 v0, v0, 0, 0
	v_add_f32_e32 v2, 0x43000000, v2
	v_cvt_pk_u8_f32 v0, v1, 1, v0
	v_add_f32_e32 v3, 0x43000000, v3
	v_cvt_pk_u8_f32 v0, v2, 2, v0
	v_cvt_pk_u8_f32 v0, v3, 3, v0
	v_xor_b32_e32 v13, 0x80808080, v0
	global_store_dwordx2 v[16:17], v[12:13], off
	s_cbranch_scc1 .LBB0_84
; #define GAS __attribute__((address_space(1)))
; __device__ __forceinline__ void phase_weights(LAS unsigned char* lds, const Ptrs& P, int wg, int G, int wv) {
;     ...
;             const GAS float* xr = (const GAS float*)P.x + (size_t)r * D + 8 * lane;
;             f32x4 v[4][2]; float ss = 0.f;
; #pragma unroll
;             for (int j = 0; j < 4; ++j)
; #pragma unroll
;                 for (int h = 0; h < 2; ++h) { v[j][h] = *(const GAS f32x4*)(xr + 512 * j + 4 * h); ss += (v[j][h][0] * v[j][h][0] + v[j][h][1] * v[j][h][1]) + (v[j][h][2] * v[j][h][2] + v[j][h][3] * v[j][h][3]); }
;             ss = wave_sum(ss);
;             if (lane < 8) rowss0[(size_t)r * 8 + lane] = lane == 0 ? ss : 0.f;
.LBB0_82:
	s_waitcnt vmcnt(0)
	s_nop 1
	v_mov_b32_e32 v28, v100
	v_mov_b32_e32 v29, v101
	v_mov_b32_e32 v30, v102
	v_mov_b32_e32 v31, v103
	v_mov_b32_e32 v24, v104
	v_mov_b32_e32 v25, v105
	v_mov_b32_e32 v26, v106
	v_mov_b32_e32 v27, v107
	v_mov_b32_e32 v20, v108
	v_mov_b32_e32 v21, v109
	v_mov_b32_e32 v22, v110
	v_mov_b32_e32 v23, v111
	v_mov_b32_e32 v16, v112
	v_mov_b32_e32 v17, v113
	v_mov_b32_e32 v18, v114
	v_mov_b32_e32 v19, v115
	v_mov_b32_e32 v12, v116
	v_mov_b32_e32 v13, v117
	v_mov_b32_e32 v14, v118
	v_mov_b32_e32 v15, v119
	v_mov_b32_e32 v8, v120
	v_mov_b32_e32 v9, v121
	v_mov_b32_e32 v10, v122
	v_mov_b32_e32 v11, v123
	v_mov_b32_e32 v4, v124
	v_mov_b32_e32 v5, v125
	v_mov_b32_e32 v6, v126
	v_mov_b32_e32 v7, v127
	v_mov_b32_e32 v0, v128
	v_mov_b32_e32 v1, v129
	v_mov_b32_e32 v2, v130
	v_mov_b32_e32 v3, v131
	s_ashr_i32 s6, s30, 12
	s_mul_hi_i32 s7, s6, 0x12000
	s_mul_i32 s6, s6, 0x12000
	s_add_u32 s6, s33, s6
	s_addc_u32 s7, s38, s7
	s_add_u32 s26, s6, 0x2000
	s_addc_u32 s27, s7, 0
	global_load_dwordx4 v[180:183], v56, s[26:27]
	global_load_dwordx4 v[212:215], v[42:43], off
	global_load_dwordx4 v[184:187], v56, s[26:27] offset:16
	global_load_dwordx4 v[216:219], v[42:43], off offset:16
	global_load_dwordx4 v[188:191], v57, s[26:27]
	global_load_dwordx4 v[220:223], v[42:43], off offset:2048
	global_load_dwordx4 v[192:195], v57, s[26:27] offset:16
	global_load_dwordx4 v[224:227], v[42:43], off offset:2064
	global_load_dwordx4 v[196:199], v58, s[26:27]
	global_load_dwordx4 v[228:231], v[44:45], off
	global_load_dwordx4 v[200:203], v58, s[26:27] offset:16
	global_load_dwordx4 v[232:235], v[44:45], off offset:16
	global_load_dwordx4 v[204:207], v59, s[26:27]
	global_load_dwordx4 v[236:239], v[46:47], off
	global_load_dwordx4 v[208:211], v59, s[26:27] offset:16
	global_load_dwordx4 v[240:243], v[46:47], off offset:16
	v_mbcnt_lo_u32_b32 v32, -1, 0
	v_mbcnt_hi_u32_b32 v32, -1, v32
	v_mul_f32_e32 v60, v29, v29
	v_mul_f32_e32 v61, v31, v31
	v_mul_f32_e32 v62, v25, v25
	v_mul_f32_e32 v63, v27, v27
	v_mul_f32_e32 v64, v21, v21
	v_mul_f32_e32 v65, v23, v23
	v_fmac_f32_e32 v60, v28, v28
	v_fmac_f32_e32 v61, v30, v30
	v_fmac_f32_e32 v62, v24, v24
	v_fmac_f32_e32 v63, v26, v26
	v_mul_f32_e32 v66, v17, v17
	v_mul_f32_e32 v67, v19, v19
	v_fmac_f32_e32 v64, v20, v20
	v_fmac_f32_e32 v65, v22, v22
	v_add_f32_e32 v60, v60, v61
	v_add_f32_e32 v61, v62, v63
	v_mul_f32_e32 v68, v13, v13
	v_mul_f32_e32 v69, v15, v15
	v_fmac_f32_e32 v66, v16, v16
	v_fmac_f32_e32 v67, v18, v18
	v_add_f32_e32 v62, v64, v65
	v_add_f32_e32 v60, v60, v61
	v_mul_f32_e32 v70, v9, v9
	v_mul_f32_e32 v71, v11, v11
	v_fmac_f32_e32 v68, v12, v12
	v_fmac_f32_e32 v69, v14, v14
	v_add_f32_e32 v63, v66, v67
	v_add_f32_e32 v60, v60, v62
	v_mul_f32_e32 v72, v5, v5
	v_mul_f32_e32 v73, v7, v7
	v_fmac_f32_e32 v70, v8, v8
	v_fmac_f32_e32 v71, v10, v10
	v_add_f32_e32 v64, v68, v69
	v_add_f32_e32 v60, v60, v63
	v_mul_f32_e32 v74, v1, v1
	v_mul_f32_e32 v75, v3, v3
	v_fmac_f32_e32 v72, v4, v4
	v_fmac_f32_e32 v73, v6, v6
	v_add_f32_e32 v65, v70, v71
	v_add_f32_e32 v60, v60, v64
	v_fmac_f32_e32 v74, v0, v0
	v_fmac_f32_e32 v75, v2, v2
	v_add_f32_e32 v66, v72, v73
	v_add_f32_e32 v60, v60, v65
	v_lshlrev_b32_e32 v32, 2, v32
	v_add_f32_e32 v67, v74, v75
	v_add_f32_e32 v60, v60, v66
	v_xor_b32_e32 v32, 4, v32
	v_add_f32_e32 v60, v60, v67
	ds_bpermute_b32 v32, v32, v60
	v_mbcnt_lo_u32_b32 v61, -1, 0
	v_mbcnt_hi_u32_b32 v61, -1, v61
	s_waitcnt lgkmcnt(0)
	v_add_f32_e32 v32, v60, v32
	v_lshlrev_b32_e32 v61, 2, v61
	v_xor_b32_e32 v61, 8, v61
	ds_bpermute_b32 v60, v61, v32
	v_mbcnt_lo_u32_b32 v61, -1, 0
	v_mbcnt_hi_u32_b32 v61, -1, v61
	s_waitcnt lgkmcnt(0)
	v_add_f32_e32 v32, v32, v60
	v_lshlrev_b32_e32 v61, 2, v61
	v_xor_b32_e32 v61, 16, v61
	ds_bpermute_b32 v60, v61, v32
	v_mbcnt_lo_u32_b32 v61, -1, 0
	v_mbcnt_hi_u32_b32 v61, -1, v61
	s_waitcnt lgkmcnt(0)
	v_add_f32_e32 v32, v32, v60
	v_lshlrev_b32_e32 v61, 2, v61
	v_xor_b32_e32 v61, 32, v61
	ds_bpermute_b32 v60, v61, v32
	v_mbcnt_lo_u32_b32 v61, -1, 0
	v_mbcnt_hi_u32_b32 v61, -1, v61
	s_waitcnt lgkmcnt(0)
	v_add_f32_e32 v32, v32, v60
	v_lshlrev_b32_e32 v61, 2, v61
	v_xor_b32_e32 v61, 64, v61
	ds_bpermute_b32 v60, v61, v32
	v_mbcnt_lo_u32_b32 v61, -1, 0
	v_mbcnt_hi_u32_b32 v61, -1, v61
	s_waitcnt lgkmcnt(0)
	v_add_f32_e32 v32, v32, v60
	v_lshlrev_b32_e32 v61, 2, v61
	v_xor_b32_e32 v60, 0x80, v61
	ds_bpermute_b32 v60, v60, v32
	s_waitcnt lgkmcnt(0)
	v_add_f32_e32 v32, v32, v60
	s_and_saveexec_b64 s[6:7], s[0:1]
	s_cbranch_execz .LBB0_81
	v_cndmask_b32_e64 v60, 0, v32, s[4:5]
	global_store_dword v[48:49], v60, off
	s_branch .LBB0_81
